# EpiFinal f32 output stores (d_out, never re-read) use the nt streaming policy
# baseline (speedup 1.0000x reference)
.LBB0_186:
	s_or_b64 exec, exec, s[18:19]
	s_waitcnt lgkmcnt(0)
	s_barrier
	v_lshl_add_u64 v[8:9], v[168:169], 2, s[42:43]
	global_load_dwordx4 v[12:15], v[8:9], off offset:16
	global_load_dwordx4 v[16:19], v[8:9], off
	s_waitcnt lgkmcnt(0)
	global_load_dwordx4 v[4:7], v[8:9], off offset:528
	s_nop 0
	global_load_dwordx4 v[8:11], v[8:9], off offset:512
	v_lshl_add_u32 v109, v2, 2, s36
	ds_read_b32 v106, v109
	v_ashrrev_i32_e32 v100, 3, v210
	v_mul_lo_u32 v101, v2, s94
	v_lshlrev_b32_e32 v102, 2, v209
	v_lshlrev_b32_e32 v2, 4, v2
	v_add3_u32 v107, s37, v101, v102
	v_and_b32_e32 v2, 0x70, v2
	v_mul_lo_u32 v101, v100, s94
	v_add3_u32 v108, s37, v2, v101
	v_ashrrev_i32_e32 v101, 31, v100
	v_lshlrev_b64 v[100:101], 12, v[100:101]
	s_mov_b64 s[18:19], 0x8000
	s_ashr_i32 s15, s14, 31
	s_ashr_i32 s17, s16, 31
	v_lshl_add_u64 v[102:103], v[100:101], 0, s[18:19]
	s_lshl_b64 s[18:19], s[14:15], 12
	s_waitcnt lgkmcnt(0)
	v_pk_mul_f32 v[104:105], v[176:177], v[106:107] op_sel_hi:[1,0]
	v_pk_mul_f32 v[110:111], v[174:175], v[106:107] op_sel_hi:[1,0]
	s_add_u32 s15, s4, s18
	s_addc_u32 s18, s5, s19
	s_lshl_b64 s[16:17], s[16:17], 2
	s_add_u32 s15, s15, s16
	s_addc_u32 s19, s18, s17
	s_add_u32 s18, s15, s63
	s_addc_u32 s19, s19, 0
	s_waitcnt vmcnt(2)
	v_pk_mul_f32 v[118:119], v[18:19], v[110:111]
	v_pk_mul_f32 v[116:117], v[16:17], v[104:105]
	v_pk_mul_f32 v[104:105], v[172:173], v[106:107] op_sel_hi:[1,0]
	v_pk_mul_f32 v[110:111], v[170:171], v[106:107] op_sel_hi:[1,0]
	ds_write_b128 v107, v[116:119]
	v_pk_mul_f32 v[118:119], v[14:15], v[110:111]
	v_pk_mul_f32 v[116:117], v[12:13], v[104:105]
	ds_write_b128 v107, v[116:119] offset:16
	ds_read_b128 v[116:119], v108
	ds_read_b128 v[120:123], v108 offset:1152
	v_lshl_add_u64 v[104:105], s[18:19], 0, v[2:3]
	v_lshl_add_u64 v[110:111], v[104:105], 0, v[100:101]
	s_waitcnt lgkmcnt(1)
	global_store_dwordx4 v[110:111], v[116:119], off nt
	v_lshl_add_u64 v[168:169], v[104:105], 0, v[102:103]
	s_waitcnt lgkmcnt(0)
	global_store_dwordx4 v[168:169], v[120:123], off nt
	v_pk_mul_f32 v[116:117], v[146:147], v[106:107] op_sel_hi:[1,0]
	v_pk_mul_f32 v[118:119], v[144:145], v[106:107] op_sel_hi:[1,0]
	s_waitcnt vmcnt(2)
	v_pk_mul_f32 v[116:117], v[8:9], v[116:117]
	v_pk_mul_f32 v[118:119], v[10:11], v[118:119]
	ds_write_b128 v107, v[116:119]
	v_pk_mul_f32 v[116:117], v[142:143], v[106:107] op_sel_hi:[1,0]
	v_pk_mul_f32 v[118:119], v[140:141], v[106:107] op_sel_hi:[1,0]
	v_pk_mul_f32 v[116:117], v[4:5], v[116:117]
	v_pk_mul_f32 v[118:119], v[6:7], v[118:119]
	ds_write_b128 v107, v[116:119] offset:16
	ds_read_b128 v[116:119], v108
	ds_read_b128 v[120:123], v108 offset:1152
	s_waitcnt lgkmcnt(1)
	global_store_dwordx4 v[110:111], v[116:119], off offset:512 nt
	s_waitcnt lgkmcnt(0)
	global_store_dwordx4 v[168:169], v[120:123], off offset:512 nt
	ds_read_b32 v106, v109 offset:64
	s_or_b32 s18, s14, 16
	s_ashr_i32 s19, s18, 31
	s_lshl_b64 s[18:19], s[18:19], 12
	s_add_u32 s15, s4, s18
	s_waitcnt lgkmcnt(0)
	v_pk_mul_f32 v[110:111], v[180:181], v[106:107] op_sel_hi:[1,0]
	v_pk_mul_f32 v[116:117], v[178:179], v[106:107] op_sel_hi:[1,0]
	s_addc_u32 s18, s5, s19
	v_pk_mul_f32 v[118:119], v[18:19], v[116:117]
	v_pk_mul_f32 v[116:117], v[16:17], v[110:111]
	ds_write_b128 v107, v[116:119]
	v_pk_mul_f32 v[110:111], v[154:155], v[106:107] op_sel_hi:[1,0]
	v_pk_mul_f32 v[116:117], v[152:153], v[106:107] op_sel_hi:[1,0]
	s_add_u32 s15, s15, s16
	v_pk_mul_f32 v[118:119], v[14:15], v[116:117]
	v_pk_mul_f32 v[116:117], v[12:13], v[110:111]
	ds_write_b128 v107, v[116:119] offset:16
	s_addc_u32 s19, s18, s17
	ds_read_b128 v[116:119], v108
	ds_read_b128 v[120:123], v108 offset:1152
	s_add_u32 s18, s15, s63
	s_addc_u32 s19, s19, 0
	v_lshl_add_u64 v[110:111], s[18:19], 0, v[2:3]
	v_lshl_add_u64 v[140:141], v[110:111], 0, v[100:101]
	s_waitcnt lgkmcnt(1)
	global_store_dwordx4 v[140:141], v[116:119], off nt
	v_lshl_add_u64 v[110:111], v[110:111], 0, v[102:103]
	s_waitcnt lgkmcnt(0)
	global_store_dwordx4 v[110:111], v[120:123], off nt
	v_pk_mul_f32 v[116:117], v[130:131], v[106:107] op_sel_hi:[1,0]
	v_pk_mul_f32 v[118:119], v[128:129], v[106:107] op_sel_hi:[1,0]
	v_pk_mul_f32 v[116:117], v[8:9], v[116:117]
	v_pk_mul_f32 v[118:119], v[10:11], v[118:119]
	ds_write_b128 v107, v[116:119]
	v_pk_mul_f32 v[116:117], v[126:127], v[106:107] op_sel_hi:[1,0]
	v_pk_mul_f32 v[118:119], v[124:125], v[106:107] op_sel_hi:[1,0]
	v_pk_mul_f32 v[116:117], v[4:5], v[116:117]
	v_pk_mul_f32 v[118:119], v[6:7], v[118:119]
	ds_write_b128 v107, v[116:119] offset:16
	ds_read_b128 v[116:119], v108
	ds_read_b128 v[120:123], v108 offset:1152
	s_waitcnt lgkmcnt(1)
	global_store_dwordx4 v[140:141], v[116:119], off offset:512 nt
	s_waitcnt lgkmcnt(0)
	global_store_dwordx4 v[110:111], v[120:123], off offset:512 nt
	ds_read_b32 v106, v109 offset:128
	s_or_b32 s18, s14, 32
	s_ashr_i32 s19, s18, 31
	s_lshl_b64 s[18:19], s[18:19], 12
	s_add_u32 s15, s4, s18
	s_waitcnt lgkmcnt(0)
	v_pk_mul_f32 v[110:111], v[150:151], v[106:107] op_sel_hi:[1,0]
	v_pk_mul_f32 v[116:117], v[148:149], v[106:107] op_sel_hi:[1,0]
	s_addc_u32 s18, s5, s19
	v_pk_mul_f32 v[118:119], v[18:19], v[116:117]
	v_pk_mul_f32 v[116:117], v[16:17], v[110:111]
	ds_write_b128 v107, v[116:119]
	v_pk_mul_f32 v[110:111], v[138:139], v[106:107] op_sel_hi:[1,0]
	v_pk_mul_f32 v[116:117], v[136:137], v[106:107] op_sel_hi:[1,0]
	s_add_u32 s15, s15, s16
	v_pk_mul_f32 v[118:119], v[14:15], v[116:117]
	v_pk_mul_f32 v[116:117], v[12:13], v[110:111]
	ds_write_b128 v107, v[116:119] offset:16
	s_addc_u32 s19, s18, s17
	ds_read_b128 v[116:119], v108
	ds_read_b128 v[120:123], v108 offset:1152
	s_add_u32 s18, s15, s63
	s_addc_u32 s19, s19, 0
	v_lshl_add_u64 v[110:111], s[18:19], 0, v[2:3]
	v_lshl_add_u64 v[124:125], v[110:111], 0, v[100:101]
	s_waitcnt lgkmcnt(1)
	global_store_dwordx4 v[124:125], v[116:119], off nt
	v_pk_mul_f32 v[96:97], v[96:97], v[106:107] op_sel_hi:[1,0]
	v_pk_mul_f32 v[92:93], v[92:93], v[106:107] op_sel_hi:[1,0]
	v_pk_mul_f32 v[116:117], v[98:99], v[106:107] op_sel_hi:[1,0]
	v_pk_mul_f32 v[98:99], v[10:11], v[96:97]
	v_pk_mul_f32 v[96:97], v[8:9], v[116:117]
	ds_write_b128 v107, v[96:99]
	v_pk_mul_f32 v[96:97], v[94:95], v[106:107] op_sel_hi:[1,0]
	v_lshl_add_u64 v[110:111], v[110:111], 0, v[102:103]
	v_pk_mul_f32 v[94:95], v[6:7], v[92:93]
	v_pk_mul_f32 v[92:93], v[4:5], v[96:97]
	s_waitcnt lgkmcnt(1)
	global_store_dwordx4 v[110:111], v[120:123], off nt
	ds_write_b128 v107, v[92:95] offset:16
	ds_read_b128 v[92:95], v108
	ds_read_b128 v[96:99], v108 offset:1152
	s_waitcnt lgkmcnt(1)
	global_store_dwordx4 v[124:125], v[92:95], off offset:512 nt
	s_waitcnt lgkmcnt(0)
	global_store_dwordx4 v[110:111], v[96:99], off offset:512 nt
	ds_read_b32 v106, v109 offset:192
	s_or_b32 s14, s14, 48
	s_ashr_i32 s15, s14, 31
	s_lshl_b64 s[14:15], s[14:15], 12
	s_add_u32 s14, s4, s14
	s_waitcnt lgkmcnt(0)
	v_pk_mul_f32 v[92:93], v[134:135], v[106:107] op_sel_hi:[1,0]
	v_pk_mul_f32 v[94:95], v[132:133], v[106:107] op_sel_hi:[1,0]
	v_pk_mul_f32 v[92:93], v[16:17], v[92:93]
	v_pk_mul_f32 v[94:95], v[18:19], v[94:95]
	ds_write_b128 v107, v[92:95]
	v_pk_mul_f32 v[92:93], v[114:115], v[106:107] op_sel_hi:[1,0]
	v_pk_mul_f32 v[94:95], v[112:113], v[106:107] op_sel_hi:[1,0]
	v_pk_mul_f32 v[92:93], v[12:13], v[92:93]
	v_pk_mul_f32 v[94:95], v[14:15], v[94:95]
	s_addc_u32 s15, s5, s15
	ds_write_b128 v107, v[92:95] offset:16
	s_add_u32 s14, s14, s16
	s_addc_u32 s15, s15, s17
	ds_read_b128 v[92:95], v108
	ds_read_b128 v[96:99], v108 offset:1152
	s_add_u32 s14, s14, s63
	s_addc_u32 s15, s15, 0
	v_lshl_add_u64 v[110:111], s[14:15], 0, v[2:3]
	v_lshl_add_u64 v[112:113], v[110:111], 0, v[100:101]
	s_waitcnt lgkmcnt(1)
	global_store_dwordx4 v[112:113], v[92:95], off nt
	v_pk_mul_f32 v[80:81], v[80:81], v[106:107] op_sel_hi:[1,0]
	v_pk_mul_f32 v[76:77], v[76:77], v[106:107] op_sel_hi:[1,0]
	v_pk_mul_f32 v[94:95], v[82:83], v[106:107] op_sel_hi:[1,0]
	v_pk_mul_f32 v[82:83], v[10:11], v[80:81]
	v_pk_mul_f32 v[80:81], v[8:9], v[94:95]
	ds_write_b128 v107, v[80:83]
	v_pk_mul_f32 v[80:81], v[78:79], v[106:107] op_sel_hi:[1,0]
	v_lshl_add_u64 v[92:93], v[110:111], 0, v[102:103]
	v_pk_mul_f32 v[78:79], v[6:7], v[76:77]
	v_pk_mul_f32 v[76:77], v[4:5], v[80:81]
	s_waitcnt lgkmcnt(1)
	global_store_dwordx4 v[92:93], v[96:99], off nt
	ds_write_b128 v107, v[76:79] offset:16
	ds_read_b128 v[76:79], v108
	ds_read_b128 v[80:83], v108 offset:1152
	s_waitcnt lgkmcnt(1)
	global_store_dwordx4 v[112:113], v[76:79], off offset:512 nt
	s_waitcnt lgkmcnt(0)
	global_store_dwordx4 v[92:93], v[80:83], off offset:512 nt
	ds_read_b32 v2, v109 offset:512
	s_mov_b64 s[14:15], 0x80000
	v_lshl_add_u64 v[76:77], v[104:105], 0, s[14:15]
	v_lshl_add_u64 v[78:79], v[76:77], 0, v[100:101]
	s_mov_b64 s[14:15], 0x90000
	s_waitcnt lgkmcnt(0)
	v_pk_mul_f32 v[64:65], v[64:65], v[2:3] op_sel_hi:[1,0]
	v_pk_mul_f32 v[66:67], v[66:67], v[2:3] op_sel_hi:[1,0]
	v_pk_mul_f32 v[60:61], v[60:61], v[2:3] op_sel_hi:[1,0]
	v_pk_mul_f32 v[62:63], v[62:63], v[2:3] op_sel_hi:[1,0]
	v_pk_mul_f32 v[66:67], v[18:19], v[66:67]
	v_pk_mul_f32 v[64:65], v[16:17], v[64:65]
	v_pk_mul_f32 v[62:63], v[14:15], v[62:63]
	v_pk_mul_f32 v[60:61], v[12:13], v[60:61]
	ds_write_b128 v107, v[64:67]
	ds_write_b128 v107, v[60:63] offset:16
	ds_read_b128 v[60:63], v108
	ds_read_b128 v[64:67], v108 offset:1152
	v_pk_mul_f32 v[56:57], v[56:57], v[2:3] op_sel_hi:[1,0]
	v_pk_mul_f32 v[58:59], v[58:59], v[2:3] op_sel_hi:[1,0]
	v_pk_mul_f32 v[52:53], v[52:53], v[2:3] op_sel_hi:[1,0]
	v_pk_mul_f32 v[54:55], v[54:55], v[2:3] op_sel_hi:[1,0]
	s_waitcnt lgkmcnt(1)
	global_store_dwordx4 v[78:79], v[60:63], off nt
	v_pk_mul_f32 v[58:59], v[10:11], v[58:59]
	v_pk_mul_f32 v[56:57], v[8:9], v[56:57]
	v_lshl_add_u64 v[60:61], v[76:77], 0, v[102:103]
	v_pk_mul_f32 v[54:55], v[6:7], v[54:55]
	v_pk_mul_f32 v[52:53], v[4:5], v[52:53]
	s_waitcnt lgkmcnt(0)
	global_store_dwordx4 v[60:61], v[64:67], off nt
	ds_write_b128 v107, v[56:59]
	ds_write_b128 v107, v[52:55] offset:16
	ds_read_b128 v[52:55], v108
	ds_read_b128 v[56:59], v108 offset:1152
	s_waitcnt lgkmcnt(1)
	global_store_dwordx4 v[78:79], v[52:55], off offset:512 nt
	s_waitcnt lgkmcnt(0)
	global_store_dwordx4 v[60:61], v[56:59], off offset:512 nt
	ds_read_b32 v2, v109 offset:576
	v_lshl_add_u64 v[52:53], v[104:105], 0, s[14:15]
	v_lshl_add_u64 v[54:55], v[52:53], 0, v[100:101]
	s_mov_b64 s[14:15], 0xa0000
	s_and_b64 vcc, exec, s[38:39]
	s_waitcnt lgkmcnt(0)
	v_pk_mul_f32 v[48:49], v[48:49], v[2:3] op_sel_hi:[1,0]
	v_pk_mul_f32 v[50:51], v[50:51], v[2:3] op_sel_hi:[1,0]
	v_pk_mul_f32 v[44:45], v[44:45], v[2:3] op_sel_hi:[1,0]
	v_pk_mul_f32 v[46:47], v[46:47], v[2:3] op_sel_hi:[1,0]
	v_pk_mul_f32 v[50:51], v[18:19], v[50:51]
	v_pk_mul_f32 v[48:49], v[16:17], v[48:49]
	v_pk_mul_f32 v[46:47], v[14:15], v[46:47]
	v_pk_mul_f32 v[44:45], v[12:13], v[44:45]
	ds_write_b128 v107, v[48:51]
	ds_write_b128 v107, v[44:47] offset:16
	ds_read_b128 v[44:47], v108
	ds_read_b128 v[48:51], v108 offset:1152
	v_pk_mul_f32 v[40:41], v[40:41], v[2:3] op_sel_hi:[1,0]
	v_pk_mul_f32 v[42:43], v[42:43], v[2:3] op_sel_hi:[1,0]
	v_pk_mul_f32 v[36:37], v[36:37], v[2:3] op_sel_hi:[1,0]
	v_pk_mul_f32 v[38:39], v[38:39], v[2:3] op_sel_hi:[1,0]
	s_waitcnt lgkmcnt(1)
	global_store_dwordx4 v[54:55], v[44:47], off nt
	v_pk_mul_f32 v[42:43], v[10:11], v[42:43]
	v_pk_mul_f32 v[40:41], v[8:9], v[40:41]
	v_lshl_add_u64 v[44:45], v[52:53], 0, v[102:103]
	v_pk_mul_f32 v[38:39], v[6:7], v[38:39]
	v_pk_mul_f32 v[36:37], v[4:5], v[36:37]
	s_waitcnt lgkmcnt(0)
	global_store_dwordx4 v[44:45], v[48:51], off nt
	ds_write_b128 v107, v[40:43]
	ds_write_b128 v107, v[36:39] offset:16
	ds_read_b128 v[36:39], v108
	ds_read_b128 v[40:43], v108 offset:1152
	s_waitcnt lgkmcnt(1)
	global_store_dwordx4 v[54:55], v[36:39], off offset:512 nt
	s_waitcnt lgkmcnt(0)
	global_store_dwordx4 v[44:45], v[40:43], off offset:512 nt
	ds_read_b32 v2, v109 offset:640
	v_lshl_add_u64 v[36:37], v[104:105], 0, s[14:15]
	v_lshl_add_u64 v[38:39], v[36:37], 0, v[100:101]
	s_mov_b64 s[14:15], 0xb0000
	s_waitcnt lgkmcnt(0)
	v_pk_mul_f32 v[32:33], v[32:33], v[2:3] op_sel_hi:[1,0]
	v_pk_mul_f32 v[34:35], v[34:35], v[2:3] op_sel_hi:[1,0]
	v_pk_mul_f32 v[28:29], v[28:29], v[2:3] op_sel_hi:[1,0]
	v_pk_mul_f32 v[30:31], v[30:31], v[2:3] op_sel_hi:[1,0]
	v_pk_mul_f32 v[34:35], v[18:19], v[34:35]
	v_pk_mul_f32 v[32:33], v[16:17], v[32:33]
	v_pk_mul_f32 v[30:31], v[14:15], v[30:31]
	v_pk_mul_f32 v[28:29], v[12:13], v[28:29]
	ds_write_b128 v107, v[32:35]
	ds_write_b128 v107, v[28:31] offset:16
	ds_read_b128 v[28:31], v108
	ds_read_b128 v[32:35], v108 offset:1152
	v_pk_mul_f32 v[24:25], v[24:25], v[2:3] op_sel_hi:[1,0]
	v_pk_mul_f32 v[26:27], v[26:27], v[2:3] op_sel_hi:[1,0]
	v_pk_mul_f32 v[20:21], v[20:21], v[2:3] op_sel_hi:[1,0]
	v_pk_mul_f32 v[22:23], v[22:23], v[2:3] op_sel_hi:[1,0]
	s_waitcnt lgkmcnt(1)
	global_store_dwordx4 v[38:39], v[28:31], off nt
	v_pk_mul_f32 v[26:27], v[10:11], v[26:27]
	v_pk_mul_f32 v[24:25], v[8:9], v[24:25]
	v_lshl_add_u64 v[28:29], v[36:37], 0, v[102:103]
	v_pk_mul_f32 v[22:23], v[6:7], v[22:23]
	v_pk_mul_f32 v[20:21], v[4:5], v[20:21]
	s_waitcnt lgkmcnt(0)
	global_store_dwordx4 v[28:29], v[32:35], off nt
	ds_write_b128 v107, v[24:27]
	ds_write_b128 v107, v[20:23] offset:16
	ds_read_b128 v[20:23], v108
	ds_read_b128 v[24:27], v108 offset:1152
	s_waitcnt lgkmcnt(1)
	global_store_dwordx4 v[38:39], v[20:23], off offset:512 nt
	s_waitcnt lgkmcnt(0)
	global_store_dwordx4 v[28:29], v[24:27], off offset:512 nt
	ds_read_b32 v2, v109 offset:704
	s_waitcnt lgkmcnt(0)
	v_pk_mul_f32 v[20:21], v[90:91], v[2:3] op_sel_hi:[1,0]
	v_pk_mul_f32 v[22:23], v[86:87], v[2:3] op_sel_hi:[1,0]
	v_pk_mul_f32 v[16:17], v[16:17], v[20:21]
	v_pk_mul_f32 v[18:19], v[18:19], v[22:23]
	ds_write_b128 v107, v[16:19]
	v_pk_mul_f32 v[16:17], v[88:89], v[2:3] op_sel_hi:[1,0]
	v_pk_mul_f32 v[18:19], v[74:75], v[2:3] op_sel_hi:[1,0]
	v_pk_mul_f32 v[12:13], v[12:13], v[16:17]
	v_pk_mul_f32 v[14:15], v[14:15], v[18:19]
	ds_write_b128 v107, v[12:15] offset:16
	ds_read_b128 v[12:15], v108
	ds_read_b128 v[16:19], v108 offset:1152
	v_lshl_add_u64 v[20:21], v[104:105], 0, s[14:15]
	v_lshl_add_u64 v[22:23], v[20:21], 0, v[100:101]
	s_waitcnt lgkmcnt(1)
	global_store_dwordx4 v[22:23], v[12:15], off nt
	s_mov_b64 s[14:15], -1
	s_nop 0
	v_lshl_add_u64 v[12:13], v[20:21], 0, v[102:103]
	s_waitcnt lgkmcnt(0)
	global_store_dwordx4 v[12:13], v[16:19], off nt
	v_pk_mul_f32 v[14:15], v[84:85], v[2:3] op_sel_hi:[1,0]
	s_nop 0
	v_pk_mul_f32 v[16:17], v[70:71], v[2:3] op_sel_hi:[1,0]
	v_pk_mul_f32 v[8:9], v[8:9], v[14:15]
	v_pk_mul_f32 v[10:11], v[10:11], v[16:17]
	ds_write_b128 v107, v[8:11]
	v_pk_mul_f32 v[8:9], v[72:73], v[2:3] op_sel_hi:[1,0]
	v_pk_mul_f32 v[10:11], v[68:69], v[2:3] op_sel_hi:[1,0]
	v_pk_mul_f32 v[4:5], v[4:5], v[8:9]
	v_pk_mul_f32 v[6:7], v[6:7], v[10:11]
	ds_write_b128 v107, v[4:7] offset:16
	ds_read_b128 v[4:7], v108
	ds_read_b128 v[8:11], v108 offset:1152
	s_waitcnt lgkmcnt(1)
	global_store_dwordx4 v[22:23], v[4:7], off offset:512 nt
	s_waitcnt lgkmcnt(0)
	global_store_dwordx4 v[12:13], v[8:11], off offset:512 nt
	s_cbranch_vccnz .LBB0_144
	s_andn2_b64 vcc, exec, s[48:49]
	s_cbranch_vccnz .LBB0_143
	s_barrier
	s_branch .LBB0_143
